# v030 + second tile: K reads issued first, next-stage LDS staging writes moved behind the QK MFMAs (all 7 attention loops)
# baseline (speedup 1.0000x reference)
; #define LAS __attribute__((address_space(3)))
; template <bool HAS_POST, class MaskF>
; __device__ __forceinline__ void attn_run(LAS unsigned char* lds, const bf16* Kg, const bf16* Vg, int pitch, int t0, int t1,
;                                          const bf16x8 (&qr)[4], f32x16& o0, f32x16& o1, f32x16& o2, MaskF& mf, const int wv) {
;     ...
;         if (more) {
;             *(LAS v4u*)(lds + ((cur ^ 1) * 2) * KBUF + kwoff) = kreg0; *(LAS v4u*)(lds + ((cur ^ 1) * 2) * VBUF + vwoff) = vreg0;
;             if (more2) { *(LAS v4u*)(lds + ((cur ^ 1) * 2 + 1) * KBUF + kwoff) = kreg1; *(LAS v4u*)(lds + ((cur ^ 1) * 2 + 1) * VBUF + vwoff) = vreg1; }
;         }
.LBB0_869:
	s_andn2_b64 vcc, exec, s[14:15]
	s_cbranch_vccnz .Lew_skip_20760
	s_xor_b32 s98, s18, 2
	s_mul_i32 s99, s98, 0x2400
	v_add_u32_e32 v228, s99, v114
	v_lshl_add_u32 v229, s98, 13, v163
	s_and_b64 vcc, exec, s[6:7]
	s_waitcnt vmcnt(1)
	ds_write_b128 v228, v[82:85]
	s_waitcnt vmcnt(0)
	ds_write_b128 v229, v[86:89] offset:36864
	s_mov_b64 s[14:15], 0
	s_cbranch_vccnz .Lew_skip_20760
	ds_write_b128 v228, v[90:93] offset:9216
	ds_write_b128 v229, v[94:97] offset:45056

; #define LAS __attribute__((address_space(3)))
; template <bool HAS_POST, class MaskF>
; __device__ __forceinline__ void attn_run(LAS unsigned char* lds, const bf16* Kg, const bf16* Vg, int pitch, int t0, int t1,
;                                          const bf16x8 (&qr)[4], f32x16& o0, f32x16& o1, f32x16& o2, MaskF& mf, const int wv) {
;     ...
;         if (more) {
;             *(LAS v4u*)(lds + ((cur ^ 1) * 2) * KBUF + kwoff) = kreg0; *(LAS v4u*)(lds + ((cur ^ 1) * 2) * VBUF + vwoff) = vreg0;
;             if (more2) { *(LAS v4u*)(lds + ((cur ^ 1) * 2 + 1) * KBUF + kwoff) = kreg1; *(LAS v4u*)(lds + ((cur ^ 1) * 2 + 1) * VBUF + vwoff) = vreg1; }
;         }
.LBB0_939:
	s_andn2_b64 vcc, exec, s[96:97]
	s_cbranch_vccnz .Lew_skip_22585
	s_xor_b32 s98, s5, 2
	s_mul_i32 s99, s98, 0x2400
	v_add_u32_e32 v228, s99, v161
	v_lshl_add_u32 v229, s98, 13, v162
	s_and_b64 vcc, exec, s[92:93]
	s_waitcnt vmcnt(1)
	ds_write_b128 v228, v[82:85]
	s_waitcnt vmcnt(0)
	ds_write_b128 v229, v[86:89] offset:36864
	s_mov_b64 s[96:97], 0
	s_cbranch_vccnz .Lew_skip_22585
	ds_write_b128 v228, v[90:93] offset:9216
	ds_write_b128 v229, v[94:97] offset:45056

; #define LAS __attribute__((address_space(3)))
; template <bool HAS_POST, class MaskF>
; __device__ __forceinline__ void attn_run(LAS unsigned char* lds, const bf16* Kg, const bf16* Vg, int pitch, int t0, int t1,
;                                          const bf16x8 (&qr)[4], f32x16& o0, f32x16& o1, f32x16& o2, MaskF& mf, const int wv) {
;     ...
;         if (more) {
;             *(LAS v4u*)(lds + ((cur ^ 1) * 2) * KBUF + kwoff) = kreg0; *(LAS v4u*)(lds + ((cur ^ 1) * 2) * VBUF + vwoff) = vreg0;
;             if (more2) { *(LAS v4u*)(lds + ((cur ^ 1) * 2 + 1) * KBUF + kwoff) = kreg1; *(LAS v4u*)(lds + ((cur ^ 1) * 2 + 1) * VBUF + vwoff) = vreg1; }
;         }
.LBB0_981:
	s_andn2_b64 vcc, exec, s[20:21]
	s_cbranch_vccnz .Lew_skip_23466
	s_xor_b32 s98, s97, 2
	s_mul_i32 s99, s98, 0x2400
	v_add_u32_e32 v228, s99, v114
	v_lshl_add_u32 v229, s98, 13, v203
	s_and_b64 vcc, exec, s[94:95]
	s_waitcnt vmcnt(1)
	ds_write_b128 v228, v[132:135]
	s_waitcnt vmcnt(0)
	ds_write_b128 v229, v[136:139] offset:36864
	s_mov_b64 s[20:21], 0
	s_cbranch_vccnz .Lew_skip_23466
	ds_write_b128 v228, v[140:143] offset:9216
	ds_write_b128 v229, v[144:147] offset:45056

; #define LAS __attribute__((address_space(3)))
; template <bool HAS_POST, class MaskF>
; __device__ __forceinline__ void attn_run(LAS unsigned char* lds, const bf16* Kg, const bf16* Vg, int pitch, int t0, int t1,
;                                          const bf16x8 (&qr)[4], f32x16& o0, f32x16& o1, f32x16& o2, MaskF& mf, const int wv) {
;     ...
;             LAS unsigned char* Kb = lds + (cur * 2 + j) * KBUF + cx.kroff;
;             if (wv < 4) __builtin_amdgcn_s_setprio(1);
; #pragma unroll
;             for (int d0 = 0; d0 < 4; ++d0) {
;                 const bf16x8 a0 = *(const LAS bf16x8*)(Kb + d0 * 32), a1 = *(const LAS bf16x8*)(Kb + 32 * 144 + d0 * 32);
;                 if (d0 == 0) { p0 = __builtin_amdgcn_mfma_f32_32x32x16_bf16(a0, qr[0], zc, 0, 0, 0); p1 = __builtin_amdgcn_mfma_f32_32x32x16_bf16(a1, qr[0], zc, 0, 0, 0); }
;                 else { p0 = __builtin_amdgcn_mfma_f32_32x32x16_bf16(a0, qr[d0], p0, 0, 0, 0); p1 = __builtin_amdgcn_mfma_f32_32x32x16_bf16(a1, qr[d0], p1, 0, 0, 0); }
;             }
;             if (wv < 4) __builtin_amdgcn_s_setprio(0);
;     ...
;         if (more) {
;             *(LAS v4u*)(lds + ((cur ^ 1) * 2) * KBUF + kwoff) = kreg0; *(LAS v4u*)(lds + ((cur ^ 1) * 2) * VBUF + vwoff) = vreg0;
;             if (more2) { *(LAS v4u*)(lds + ((cur ^ 1) * 2 + 1) * KBUF + kwoff) = kreg1; *(LAS v4u*)(lds + ((cur ^ 1) * 2 + 1) * VBUF + vwoff) = vreg1; }
;         }
.LBB0_1192:
	s_andn2_b64 s[10:11], exec, s[24:25]
	s_andn2_b64 vcc, exec, s[24:25]
	s_cbranch_vccnz .LBB0_1194
	s_setprio 1
.LBB0_1194:
	s_or_b32 s0, s59, 1
	s_mul_i32 s1, s0, 0x2400
	v_add_u32_e32 v124, s1, v165
	ds_read_b128 v[48:51], v124
	ds_read_b128 v[120:123], v124 offset:32
	ds_read_b128 v[64:67], v124 offset:4608
	ds_read_b128 v[128:131], v124 offset:4640
	ds_read_b128 v[132:135], v124 offset:64
	ds_read_b128 v[136:139], v124 offset:4672
	ds_read_b128 v[140:143], v124 offset:96
	ds_read_b128 v[144:147], v124 offset:4704
	s_and_b64 vcc, exec, s[10:11]
	s_waitcnt lgkmcnt(7)
	v_mfma_f32_32x32x16_bf16 v[48:63], v[48:51], v[80:83], 0
	s_waitcnt lgkmcnt(6)
	v_mfma_f32_32x32x16_bf16 v[48:63], v[120:123], v[84:87], v[48:63]
	s_waitcnt lgkmcnt(5)
	v_mfma_f32_32x32x16_bf16 v[64:79], v[64:67], v[80:83], 0
	s_waitcnt lgkmcnt(4)
	v_mfma_f32_32x32x16_bf16 v[64:79], v[128:131], v[84:87], v[64:79]
	s_waitcnt lgkmcnt(3)
	v_mfma_f32_32x32x16_bf16 v[48:63], v[132:135], v[88:91], v[48:63]
	s_waitcnt lgkmcnt(2)
	v_mfma_f32_32x32x16_bf16 v[64:79], v[136:139], v[88:91], v[64:79]
	s_waitcnt lgkmcnt(1)
	v_mfma_f32_32x32x16_bf16 v[48:63], v[140:143], v[92:95], v[48:63]
	s_waitcnt lgkmcnt(0)
	v_mfma_f32_32x32x16_bf16 v[64:79], v[144:147], v[92:95], v[64:79]
	s_cbranch_vccnz .LBB0_1196
	s_setprio 0
.LBB0_1196:
	s_andn2_b64 vcc, exec, s[4:5]
	s_cbranch_vccnz .Lew_skip_29169
	s_xor_b32 s98, s59, 2
	s_mul_i32 s99, s98, 0x2400
	v_add_u32_e32 v174, s99, v160
	v_lshl_add_u32 v175, s98, 13, v161
	s_and_b64 vcc, exec, s[6:7]
	s_waitcnt vmcnt(1)
	ds_write_b128 v174, v[96:99]
	s_waitcnt vmcnt(0)
	ds_write_b128 v175, v[100:103] offset:36864
	s_mov_b64 s[4:5], 0
	s_cbranch_vccnz .Lew_skip_29169
	ds_write_b128 v174, v[104:107] offset:9216
	ds_write_b128 v175, v[108:111] offset:45056
